# dense attention epilogue: bf16 pairs staged through LDS (ds_write_b32) and written with global_store_dwordx4 instead of 128 global_store_short per lane
# speedup vs baseline: 1.0173x; 1.0007x over previous
; __device__ __forceinline__ int crow(int r, int hi) { return (r & 3) + 8 * (r >> 2) + 4 * hi; }
; __device__ __forceinline__ unsigned cvtpk(float lo, float hi) { f32x2a v = {lo, hi}; bf16x2a b = __builtin_convertvector(v, bf16x2a); return __builtin_bit_cast(unsigned, b); }
; template <int LDO>
; __device__ __forceinline__ void attn_unit_dv(const bf16_t* __restrict__ Qb, const bf16_t* __restrict__ Kh, const bf16_t* __restrict__ Vh, bf16_t* __restrict__ Ob, int NT, char* lds, LAS3 unsigned char* ldsl) {
;     ...
;   if (hi == 0) li_l[r32] = l_reg; asm volatile("s_waitcnt lgkmcnt(0)" ::: "memory");
;   float rli[16];
; #pragma unroll
;   for (int r = 0; r < 16; ++r) rli[r] = __builtin_amdgcn_rcpf(li_l[crow(r, hi)]);
;   bf16_t* Ow = Ob + (long)(wid * QBLK) * LDO;
; #pragma unroll
;   for (int r = 0; r < 16; ++r) { const int orow = crow(r, hi);
; #pragma unroll
;     for (int d0 = 0; d0 < 8; ++d0) Ow[(long)orow * LDO + d0 * 32 + r32] = (bf16_t)(cvtpk(o[d0][r] * rli[r], 0.f) & 0xffffu); }
.LBB0_639:
	s_or_b64 exec, exec, s[0:1]
	s_waitcnt lgkmcnt(0)
	v_add_u32_e32 v0, s67, v223
	ds_read_b128 v[130:133], v0
	ds_read_b128 v[134:137], v0 offset:32
	ds_read_b128 v[138:141], v0 offset:64
	ds_read_b128 v[142:145], v0 offset:96
	s_lshl_b32 s0, s34, 12
	s_lshl_b32 s1, s31, 26
	s_or_b32 s0, s1, s0
	s_add_u32 s0, s16, s0
	s_addc_u32 s1, s17, 0
	s_lshl_b32 s30, s30, 10
	s_add_u32 s0, s0, s30
	s_addc_u32 s1, s1, 0
	s_lshl_b32 s29, s29, 9
	s_add_u32 s29, s0, s29
	s_addc_u32 s30, s1, 0
	s_lshl_b64 s[0:1], s[4:5], 12
	s_add_u32 s0, s29, s0
	s_addc_u32 s1, s30, s1
	s_lshl_b32 s33, s99, 8
	s_mov_b32 s98, 0x5040100
	s_mov_b32 s100, 0x7060302
	v_lshlrev_b32_e32 v148, 11, v208
	v_lshl_add_u32 v148, v198, 2, v148
	v_add_u32_e32 v148, s33, v148
	v_lshlrev_b32_e32 v149, 10, v208
	v_lshl_add_u32 v149, v198, 5, v149
	v_add_u32_e32 v149, s33, v149
	v_lshlrev_b32_e32 v160, 13, v208
	v_lshl_add_u32 v160, v198, 4, v160
	v_mov_b32_e32 v161, v1
	v_lshl_add_u64 v[150:151], s[0:1], 0, v[160:161]
	s_mov_b64 s[0:1], 0x1000
	v_lshl_add_u64 v[158:159], v[150:151], 0, s[0:1]
	s_waitcnt lgkmcnt(0)
	v_rcp_f32_e32 v232, v130
	v_rcp_f32_e32 v233, v131
	v_rcp_f32_e32 v234, v132
	v_rcp_f32_e32 v235, v133
	v_rcp_f32_e32 v236, v134
	v_rcp_f32_e32 v237, v135
	v_rcp_f32_e32 v238, v136
	v_rcp_f32_e32 v239, v137
	v_rcp_f32_e32 v246, v138
	v_rcp_f32_e32 v247, v139
	v_rcp_f32_e32 v248, v140
	v_rcp_f32_e32 v249, v141
	v_rcp_f32_e32 v250, v142
	v_rcp_f32_e32 v251, v143
	v_rcp_f32_e32 v252, v144
	v_rcp_f32_e32 v253, v145
	s_nop 1
	v_mul_f32_e32 v146, v114, v232
	v_mul_f32_e32 v147, v115, v233
	v_cvt_pk_bf16_f32 v146, v146, v147
	ds_write_b32 v148, v146
	v_mul_f32_e32 v152, v98, v232
	v_mul_f32_e32 v153, v99, v233
	v_cvt_pk_bf16_f32 v152, v152, v153
	ds_write_b32 v148, v152 offset:128
	v_mul_f32_e32 v154, v82, v232
	v_mul_f32_e32 v155, v83, v233
	v_cvt_pk_bf16_f32 v154, v154, v155
	ds_write_b32 v148, v154 offset:256
	v_mul_f32_e32 v156, v66, v232
	v_mul_f32_e32 v157, v67, v233
	v_cvt_pk_bf16_f32 v156, v156, v157
	ds_write_b32 v148, v156 offset:384
	v_mul_f32_e32 v146, v50, v232
	v_mul_f32_e32 v147, v51, v233
	v_cvt_pk_bf16_f32 v146, v146, v147
	ds_write_b32 v148, v146 offset:512
	v_mul_f32_e32 v152, v34, v232
	v_mul_f32_e32 v153, v35, v233
	v_cvt_pk_bf16_f32 v152, v152, v153
	ds_write_b32 v148, v152 offset:640
	v_mul_f32_e32 v154, v18, v232
	v_mul_f32_e32 v155, v19, v233
	v_cvt_pk_bf16_f32 v154, v154, v155
	ds_write_b32 v148, v154 offset:768
	v_mul_f32_e32 v156, v2, v232
	v_mul_f32_e32 v157, v3, v233
	v_cvt_pk_bf16_f32 v156, v156, v157
	ds_write_b32 v148, v156 offset:896
	v_mul_f32_e32 v146, v116, v234
	v_mul_f32_e32 v147, v117, v235
	v_cvt_pk_bf16_f32 v146, v146, v147
	ds_write_b32 v148, v146 offset:1024
	v_mul_f32_e32 v152, v100, v234
	v_mul_f32_e32 v153, v101, v235
	v_cvt_pk_bf16_f32 v152, v152, v153
	ds_write_b32 v148, v152 offset:1152
	v_mul_f32_e32 v154, v84, v234
	v_mul_f32_e32 v155, v85, v235
	v_cvt_pk_bf16_f32 v154, v154, v155
	ds_write_b32 v148, v154 offset:1280
	v_mul_f32_e32 v156, v68, v234
	v_mul_f32_e32 v157, v69, v235
	v_cvt_pk_bf16_f32 v156, v156, v157
	ds_write_b32 v148, v156 offset:1408
	v_mul_f32_e32 v146, v52, v234
	v_mul_f32_e32 v147, v53, v235
	v_cvt_pk_bf16_f32 v146, v146, v147
	ds_write_b32 v148, v146 offset:1536
	v_mul_f32_e32 v152, v36, v234
	v_mul_f32_e32 v153, v37, v235
	v_cvt_pk_bf16_f32 v152, v152, v153
	ds_write_b32 v148, v152 offset:1664
	v_mul_f32_e32 v154, v20, v234
	v_mul_f32_e32 v155, v21, v235
	v_cvt_pk_bf16_f32 v154, v154, v155
	ds_write_b32 v148, v154 offset:1792
	v_mul_f32_e32 v156, v4, v234
	v_mul_f32_e32 v157, v5, v235
	v_cvt_pk_bf16_f32 v156, v156, v157
	ds_write_b32 v148, v156 offset:1920
	v_mul_f32_e32 v146, v118, v236
	v_mul_f32_e32 v147, v119, v237
	v_cvt_pk_bf16_f32 v146, v146, v147
	ds_write_b32 v148, v146 offset:4096
	v_mul_f32_e32 v152, v102, v236
	v_mul_f32_e32 v153, v103, v237
	v_cvt_pk_bf16_f32 v152, v152, v153
	ds_write_b32 v148, v152 offset:4224
	v_mul_f32_e32 v154, v86, v236
	v_mul_f32_e32 v155, v87, v237
	v_cvt_pk_bf16_f32 v154, v154, v155
	ds_write_b32 v148, v154 offset:4352
	v_mul_f32_e32 v156, v70, v236
	v_mul_f32_e32 v157, v71, v237
	v_cvt_pk_bf16_f32 v156, v156, v157
	ds_write_b32 v148, v156 offset:4480
	v_mul_f32_e32 v146, v54, v236
	v_mul_f32_e32 v147, v55, v237
	v_cvt_pk_bf16_f32 v146, v146, v147
	ds_write_b32 v148, v146 offset:4608
	v_mul_f32_e32 v152, v38, v236
	v_mul_f32_e32 v153, v39, v237
	v_cvt_pk_bf16_f32 v152, v152, v153
	ds_write_b32 v148, v152 offset:4736
	v_mul_f32_e32 v154, v22, v236
	v_mul_f32_e32 v155, v23, v237
	v_cvt_pk_bf16_f32 v154, v154, v155
	ds_write_b32 v148, v154 offset:4864
	v_mul_f32_e32 v156, v6, v236
	v_mul_f32_e32 v157, v7, v237
	v_cvt_pk_bf16_f32 v156, v156, v157
	ds_write_b32 v148, v156 offset:4992
	v_mul_f32_e32 v146, v120, v238
	v_mul_f32_e32 v147, v121, v239
	v_cvt_pk_bf16_f32 v146, v146, v147
	ds_write_b32 v148, v146 offset:5120
	v_mul_f32_e32 v152, v104, v238
	v_mul_f32_e32 v153, v105, v239
	v_cvt_pk_bf16_f32 v152, v152, v153
	ds_write_b32 v148, v152 offset:5248
	v_mul_f32_e32 v154, v88, v238
	v_mul_f32_e32 v155, v89, v239
	v_cvt_pk_bf16_f32 v154, v154, v155
	ds_write_b32 v148, v154 offset:5376
	v_mul_f32_e32 v156, v72, v238
	v_mul_f32_e32 v157, v73, v239
	v_cvt_pk_bf16_f32 v156, v156, v157
	ds_write_b32 v148, v156 offset:5504
	v_mul_f32_e32 v146, v56, v238
	v_mul_f32_e32 v147, v57, v239
	v_cvt_pk_bf16_f32 v146, v146, v147
	ds_write_b32 v148, v146 offset:5632
	v_mul_f32_e32 v152, v40, v238
	v_mul_f32_e32 v153, v41, v239
	v_cvt_pk_bf16_f32 v152, v152, v153
	ds_write_b32 v148, v152 offset:5760
	v_mul_f32_e32 v154, v24, v238
	v_mul_f32_e32 v155, v25, v239
	v_cvt_pk_bf16_f32 v154, v154, v155
; __device__ __forceinline__ int crow(int r, int hi) { return (r & 3) + 8 * (r >> 2) + 4 * hi; }
; __device__ __forceinline__ unsigned cvtpk(float lo, float hi) { f32x2a v = {lo, hi}; bf16x2a b = __builtin_convertvector(v, bf16x2a); return __builtin_bit_cast(unsigned, b); }
; template <int LDO>
; __device__ __forceinline__ void attn_unit_dv(const bf16_t* __restrict__ Qb, const bf16_t* __restrict__ Kh, const bf16_t* __restrict__ Vh, bf16_t* __restrict__ Ob, int NT, char* lds, LAS3 unsigned char* ldsl) {
;     ...
;   for (int r = 0; r < 16; ++r) rli[r] = __builtin_amdgcn_rcpf(li_l[crow(r, hi)]);
;   bf16_t* Ow = Ob + (long)(wid * QBLK) * LDO;
; #pragma unroll
;   for (int r = 0; r < 16; ++r) { const int orow = crow(r, hi);
; #pragma unroll
;     for (int d0 = 0; d0 < 8; ++d0) Ow[(long)orow * LDO + d0 * 32 + r32] = (bf16_t)(cvtpk(o[d0][r] * rli[r], 0.f) & 0xffffu); }
	ds_write_b32 v148, v154 offset:5888
	v_mul_f32_e32 v156, v8, v238
	v_mul_f32_e32 v157, v9, v239
	v_cvt_pk_bf16_f32 v156, v156, v157
	ds_write_b32 v148, v156 offset:6016
	v_mul_f32_e32 v146, v122, v246
	v_mul_f32_e32 v147, v123, v247
	v_cvt_pk_bf16_f32 v146, v146, v147
	ds_write_b32 v148, v146 offset:8192
	v_mul_f32_e32 v152, v106, v246
	v_mul_f32_e32 v153, v107, v247
	v_cvt_pk_bf16_f32 v152, v152, v153
	ds_write_b32 v148, v152 offset:8320
	v_mul_f32_e32 v154, v90, v246
	v_mul_f32_e32 v155, v91, v247
	v_cvt_pk_bf16_f32 v154, v154, v155
	ds_write_b32 v148, v154 offset:8448
	v_mul_f32_e32 v156, v74, v246
	v_mul_f32_e32 v157, v75, v247
	v_cvt_pk_bf16_f32 v156, v156, v157
	ds_write_b32 v148, v156 offset:8576
	v_mul_f32_e32 v146, v58, v246
	v_mul_f32_e32 v147, v59, v247
	v_cvt_pk_bf16_f32 v146, v146, v147
	ds_write_b32 v148, v146 offset:8704
	v_mul_f32_e32 v152, v42, v246
	v_mul_f32_e32 v153, v43, v247
	v_cvt_pk_bf16_f32 v152, v152, v153
	ds_write_b32 v148, v152 offset:8832
	v_mul_f32_e32 v154, v26, v246
	v_mul_f32_e32 v155, v27, v247
	v_cvt_pk_bf16_f32 v154, v154, v155
	ds_write_b32 v148, v154 offset:8960
	v_mul_f32_e32 v156, v10, v246
	v_mul_f32_e32 v157, v11, v247
	v_cvt_pk_bf16_f32 v156, v156, v157
	ds_write_b32 v148, v156 offset:9088
	v_mul_f32_e32 v146, v124, v248
	v_mul_f32_e32 v147, v125, v249
	v_cvt_pk_bf16_f32 v146, v146, v147
	ds_write_b32 v148, v146 offset:9216
	v_mul_f32_e32 v152, v108, v248
	v_mul_f32_e32 v153, v109, v249
	v_cvt_pk_bf16_f32 v152, v152, v153
	ds_write_b32 v148, v152 offset:9344
	v_mul_f32_e32 v154, v92, v248
	v_mul_f32_e32 v155, v93, v249
	v_cvt_pk_bf16_f32 v154, v154, v155
	ds_write_b32 v148, v154 offset:9472
	v_mul_f32_e32 v156, v76, v248
	v_mul_f32_e32 v157, v77, v249
	v_cvt_pk_bf16_f32 v156, v156, v157
	ds_write_b32 v148, v156 offset:9600
	v_mul_f32_e32 v146, v60, v248
	v_mul_f32_e32 v147, v61, v249
	v_cvt_pk_bf16_f32 v146, v146, v147
	ds_write_b32 v148, v146 offset:9728
	v_mul_f32_e32 v152, v44, v248
	v_mul_f32_e32 v153, v45, v249
	v_cvt_pk_bf16_f32 v152, v152, v153
	ds_write_b32 v148, v152 offset:9856
	v_mul_f32_e32 v154, v28, v248
	v_mul_f32_e32 v155, v29, v249
	v_cvt_pk_bf16_f32 v154, v154, v155
	ds_write_b32 v148, v154 offset:9984
	v_mul_f32_e32 v156, v12, v248
	v_mul_f32_e32 v157, v13, v249
	v_cvt_pk_bf16_f32 v156, v156, v157
	ds_write_b32 v148, v156 offset:10112
	v_mul_f32_e32 v146, v126, v250
	v_mul_f32_e32 v147, v127, v251
	v_cvt_pk_bf16_f32 v146, v146, v147
	ds_write_b32 v148, v146 offset:12288
	v_mul_f32_e32 v152, v110, v250
	v_mul_f32_e32 v153, v111, v251
	v_cvt_pk_bf16_f32 v152, v152, v153
	ds_write_b32 v148, v152 offset:12416
	v_mul_f32_e32 v154, v94, v250
	v_mul_f32_e32 v155, v95, v251
	v_cvt_pk_bf16_f32 v154, v154, v155
	ds_write_b32 v148, v154 offset:12544
	v_mul_f32_e32 v156, v78, v250
	v_mul_f32_e32 v157, v79, v251
	v_cvt_pk_bf16_f32 v156, v156, v157
	ds_write_b32 v148, v156 offset:12672
	v_mul_f32_e32 v146, v62, v250
	v_mul_f32_e32 v147, v63, v251
	v_cvt_pk_bf16_f32 v146, v146, v147
	ds_write_b32 v148, v146 offset:12800
	v_mul_f32_e32 v152, v46, v250
	v_mul_f32_e32 v153, v47, v251
	v_cvt_pk_bf16_f32 v152, v152, v153
	ds_write_b32 v148, v152 offset:12928
	v_mul_f32_e32 v154, v30, v250
	v_mul_f32_e32 v155, v31, v251
	v_cvt_pk_bf16_f32 v154, v154, v155
	ds_write_b32 v148, v154 offset:13056
	v_mul_f32_e32 v156, v14, v250
	v_mul_f32_e32 v157, v15, v251
	v_cvt_pk_bf16_f32 v156, v156, v157
	ds_write_b32 v148, v156 offset:13184
	v_mul_f32_e32 v146, v128, v252
	v_mul_f32_e32 v147, v129, v253
	v_cvt_pk_bf16_f32 v146, v146, v147
	ds_write_b32 v148, v146 offset:13312
	v_mul_f32_e32 v152, v112, v252
	v_mul_f32_e32 v153, v113, v253
	v_cvt_pk_bf16_f32 v152, v152, v153
	ds_write_b32 v148, v152 offset:13440
	v_mul_f32_e32 v154, v96, v252
	v_mul_f32_e32 v155, v97, v253
	v_cvt_pk_bf16_f32 v154, v154, v155
	ds_write_b32 v148, v154 offset:13568
	v_mul_f32_e32 v156, v80, v252
	v_mul_f32_e32 v157, v81, v253
	v_cvt_pk_bf16_f32 v156, v156, v157
	ds_write_b32 v148, v156 offset:13696
	v_mul_f32_e32 v146, v64, v252
	v_mul_f32_e32 v147, v65, v253
	v_cvt_pk_bf16_f32 v146, v146, v147
	ds_write_b32 v148, v146 offset:13824
	v_mul_f32_e32 v152, v48, v252
	v_mul_f32_e32 v153, v49, v253
	v_cvt_pk_bf16_f32 v152, v152, v153
	ds_write_b32 v148, v152 offset:13952
	v_mul_f32_e32 v154, v32, v252
	v_mul_f32_e32 v155, v33, v253
	v_cvt_pk_bf16_f32 v154, v154, v155
	ds_write_b32 v148, v154 offset:14080
	v_mul_f32_e32 v156, v16, v252
	v_mul_f32_e32 v157, v17, v253
	v_cvt_pk_bf16_f32 v156, v156, v157
	ds_write_b32 v148, v156 offset:14208
	s_waitcnt lgkmcnt(0)
	ds_read_b128 v[2:5], v149
	ds_read_b128 v[6:9], v149 offset:16
	ds_read_b128 v[10:13], v149 offset:2048
	ds_read_b128 v[14:17], v149 offset:2064
	ds_read_b128 v[18:21], v149 offset:4096
	ds_read_b128 v[22:25], v149 offset:4112
	ds_read_b128 v[26:29], v149 offset:6144
	ds_read_b128 v[30:33], v149 offset:6160
	ds_read_b128 v[34:37], v149 offset:8192
	ds_read_b128 v[38:41], v149 offset:8208
	ds_read_b128 v[42:45], v149 offset:10240
	ds_read_b128 v[46:49], v149 offset:10256
	ds_read_b128 v[50:53], v149 offset:12288
	ds_read_b128 v[54:57], v149 offset:12304
	ds_read_b128 v[58:61], v149 offset:14336
	ds_read_b128 v[62:65], v149 offset:14352
	s_mov_b64 s[0:1], 0x4000
	s_waitcnt lgkmcnt(0)
	s_barrier
; __device__ __forceinline__ int crow(int r, int hi) { return (r & 3) + 8 * (r >> 2) + 4 * hi; }
; __device__ __forceinline__ unsigned cvtpk(float lo, float hi) { f32x2a v = {lo, hi}; bf16x2a b = __builtin_convertvector(v, bf16x2a); return __builtin_bit_cast(unsigned, b); }
; template <int LDO>
; __device__ __forceinline__ void attn_unit_dv(const bf16_t* __restrict__ Qb, const bf16_t* __restrict__ Kh, const bf16_t* __restrict__ Vh, bf16_t* __restrict__ Ob, int NT, char* lds, LAS3 unsigned char* ldsl) {
;     ...
; #pragma unroll
;   for (int r = 0; r < 16; ++r) { const int orow = crow(r, hi);
; #pragma unroll
;     for (int d0 = 0; d0 < 8; ++d0) Ow[(long)orow * LDO + d0 * 32 + r32] = (bf16_t)(cvtpk(o[d0][r] * rli[r], 0.f) & 0xffffu); }
; __global__ void __launch_bounds__(NWAVES * 64, 2) mk_fwd(Args args) {
;     ...
;         for (int id2 = vcu; id2 < 1024 * ATT_REP; id2 += G) { const int id = id2 & 1023;
;             const int combo = id >> 6, qb = id & 63, b = combo >> 3, h = (combo >> 1) & 3, c = combo & 1;
;             const bf16* Q = QB + ((size_t)(b * 8 + h * 2 + c) * SEQ + qb * 256) * 128;
;             const bf16* K = KB + ((size_t)(b * 8 + h * 2 + c) * SEQ) * 128;
;             const bf16* V = VB + ((size_t)(b * 4 + h) * SEQ) * 256;
;             bf16* O = RC + (size_t)(b * SEQ + qb * 256) * 2048 + h * 512 + c * 256;
;             att::attn_unit_dv<2048>(Q, K, V, O, SEQ / 64, (char*)lds, ldsl);
;         }
	v_perm_b32 v130, v3, v2, s98
	v_perm_b32 v131, v5, v4, s98
	v_perm_b32 v132, v7, v6, s98
	v_perm_b32 v133, v9, v8, s98
	v_perm_b32 v134, v3, v2, s100
	v_perm_b32 v135, v5, v4, s100
	v_perm_b32 v136, v7, v6, s100
	v_perm_b32 v137, v9, v8, s100
	global_store_dwordx4 v[150:151], v[130:133], off
	global_store_dwordx4 v[158:159], v[134:137], off
	v_lshl_add_u64 v[150:151], v[150:151], 0, s[0:1]
	v_lshl_add_u64 v[158:159], v[158:159], 0, s[0:1]
	v_perm_b32 v138, v11, v10, s98
	v_perm_b32 v139, v13, v12, s98
	v_perm_b32 v140, v15, v14, s98
	v_perm_b32 v141, v17, v16, s98
	v_perm_b32 v142, v11, v10, s100
	v_perm_b32 v143, v13, v12, s100
	v_perm_b32 v144, v15, v14, s100
	v_perm_b32 v145, v17, v16, s100
	global_store_dwordx4 v[150:151], v[138:141], off
	global_store_dwordx4 v[158:159], v[142:145], off
	v_lshl_add_u64 v[150:151], v[150:151], 0, s[0:1]
	v_lshl_add_u64 v[158:159], v[158:159], 0, s[0:1]
	v_perm_b32 v130, v19, v18, s98
	v_perm_b32 v131, v21, v20, s98
	v_perm_b32 v132, v23, v22, s98
	v_perm_b32 v133, v25, v24, s98
	v_perm_b32 v134, v19, v18, s100
	v_perm_b32 v135, v21, v20, s100
	v_perm_b32 v136, v23, v22, s100
	v_perm_b32 v137, v25, v24, s100
	global_store_dwordx4 v[150:151], v[130:133], off
	global_store_dwordx4 v[158:159], v[134:137], off
	v_lshl_add_u64 v[150:151], v[150:151], 0, s[0:1]
	v_lshl_add_u64 v[158:159], v[158:159], 0, s[0:1]
	v_perm_b32 v138, v27, v26, s98
	v_perm_b32 v139, v29, v28, s98
	v_perm_b32 v140, v31, v30, s98
	v_perm_b32 v141, v33, v32, s98
	v_perm_b32 v142, v27, v26, s100
	v_perm_b32 v143, v29, v28, s100
	v_perm_b32 v144, v31, v30, s100
	v_perm_b32 v145, v33, v32, s100
	global_store_dwordx4 v[150:151], v[138:141], off
	global_store_dwordx4 v[158:159], v[142:145], off
	v_lshl_add_u64 v[150:151], v[150:151], 0, s[0:1]
	v_lshl_add_u64 v[158:159], v[158:159], 0, s[0:1]
	v_perm_b32 v130, v35, v34, s98
	v_perm_b32 v131, v37, v36, s98
	v_perm_b32 v132, v39, v38, s98
	v_perm_b32 v133, v41, v40, s98
	v_perm_b32 v134, v35, v34, s100
	v_perm_b32 v135, v37, v36, s100
	v_perm_b32 v136, v39, v38, s100
	v_perm_b32 v137, v41, v40, s100
	global_store_dwordx4 v[150:151], v[130:133], off
	global_store_dwordx4 v[158:159], v[134:137], off
	v_lshl_add_u64 v[150:151], v[150:151], 0, s[0:1]
	v_lshl_add_u64 v[158:159], v[158:159], 0, s[0:1]
	v_perm_b32 v138, v43, v42, s98
	v_perm_b32 v139, v45, v44, s98
	v_perm_b32 v140, v47, v46, s98
	v_perm_b32 v141, v49, v48, s98
	v_perm_b32 v142, v43, v42, s100
	v_perm_b32 v143, v45, v44, s100
	v_perm_b32 v144, v47, v46, s100
	v_perm_b32 v145, v49, v48, s100
	global_store_dwordx4 v[150:151], v[138:141], off
	global_store_dwordx4 v[158:159], v[142:145], off
	v_lshl_add_u64 v[150:151], v[150:151], 0, s[0:1]
	v_lshl_add_u64 v[158:159], v[158:159], 0, s[0:1]
	v_perm_b32 v130, v51, v50, s98
	v_perm_b32 v131, v53, v52, s98
	v_perm_b32 v132, v55, v54, s98
	v_perm_b32 v133, v57, v56, s98
	v_perm_b32 v134, v51, v50, s100
	v_perm_b32 v135, v53, v52, s100
	v_perm_b32 v136, v55, v54, s100
	v_perm_b32 v137, v57, v56, s100
	global_store_dwordx4 v[150:151], v[130:133], off
	global_store_dwordx4 v[158:159], v[134:137], off
	v_lshl_add_u64 v[150:151], v[150:151], 0, s[0:1]
	v_lshl_add_u64 v[158:159], v[158:159], 0, s[0:1]
	v_perm_b32 v138, v59, v58, s98
	v_perm_b32 v139, v61, v60, s98
	v_perm_b32 v140, v63, v62, s98
	v_perm_b32 v141, v65, v64, s98
	v_perm_b32 v142, v59, v58, s100
	v_perm_b32 v143, v61, v60, s100
	v_perm_b32 v144, v63, v62, s100
	v_perm_b32 v145, v65, v64, s100
	global_store_dwordx4 v[150:151], v[138:141], off
	global_store_dwordx4 v[158:159], v[142:145], off
	v_lshlrev_b32_e32 v0, 1, v198
	s_add_i32 s28, s28, s96
	s_cmpk_lt_i32 s28, 0x400
	s_cbranch_scc0 .LBB0_653
